# v020
# speedup vs baseline: 1.0093x; 1.0093x over previous
; __device__ __forceinline__ int otid(int wvs) { int l; asm volatile("v_mbcnt_lo_u32_b32 %0, -1, 0\n\tv_mbcnt_hi_u32_b32 %0, -1, %0" : "=v"(l)); return wvs * 64 + l; }
; __device__ __forceinline__ int v_rd_base(int lane) { return ((lane & 3) << 3) | (((lane >> 2) & 3) << 6) | (((lane >> 4) & 1) << 5) | (((lane >> 5) & 1) << 8); }
; #define TBAR(n) do { asm volatile("s_waitcnt vmcnt(" #n ") lgkmcnt(0)" ::: "memory"); __builtin_amdgcn_s_barrier(); SBAR(); } while (0)
; __device__ __forceinline__ void attn_body(const u16* __restrict__ Qb, const u16* __restrict__ Kh, const u16* __restrict__ Vh,
;                                           u16* __restrict__ Ob, int seq, int wvs) {
;     ...
;   const int tid = otid(wvs), wid = tid >> 6, lane = tid & 63, r32 = lane & 31, hi = lane >> 5;
;   char* V_lds = lds; char* K_lds = lds + 3 * SHM_V;
;   float* ws = (float*)(lds + 3 * SHM_V + 3 * SHM_K) + wid * 64; float* li_l = ws; float* al_l = ws + 32;
;   float m_reg = -1e30f, l_reg = 0; f32x16 o[4] = {}; bf16x8 qr[12];
;   const u16* Qw = Qb + (long)(wid * QBLK + r32) * 192 + hi * 8;
; #pragma unroll
;   for (int d0 = 0; d0 < 12; ++d0) qr[d0] = *reinterpret_cast<const bf16x8*>(Qw + d0 * 16);
;   unsigned kso0, kso1, kso2, vso0, vso1;
;   { int p = tid * 16, row = p / 384, pc = p - row * 384; kso0 = row * 384 + (pc ^ (((row >> 1) & 7) << 4));
;     p = 8192 + tid * 16; row = p / 384; pc = p - row * 384; kso1 = row * 384 + (pc ^ (((row >> 1) & 7) << 4));
;     p = 16384 + tid * 16; row = p / 384; pc = p - row * 384; kso2 = row * 384 + (pc ^ (((row >> 1) & 7) << 4)); }
;   { int p = tid * 16, sub = p >> 9, w = p & 511, kk = (sub >> 2) * 8 + (w >> 6), c = (sub & 3) * 32 + ((w & 63) >> 1);
;     int k = (kk & ~0xC) | ((kk & 4) << 1) | ((kk & 8) >> 1); vso0 = k * 256 + c * 2;
;     p = 8192 + tid * 16; sub = p >> 9; w = p & 511; kk = (sub >> 2) * 8 + (w >> 6); c = (sub & 3) * 32 + ((w & 63) >> 1);
;     k = (kk & ~0xC) | ((kk & 4) << 1) | ((kk & 8) >> 1); vso1 = k * 256 + c * 2; }
;   const int vb0 = (int)(uintptr_t)V_lds + v_rd_base(lane);
;     ...
;   f32x16 pA0, pA1, pB0, pB1; float mnA, mnB, alA, alB; bf16x8 pa0, pa1, pa2, pa3; const int NT = seq / KVBLK;
;   ISSUE_K(0, 0); ISSUE_V(0, 0); ISSUE_K(1, 1);
;   TBAR(5);
;   ISSUE_K(2, 2); ISSUE_V(1, 1);
;   qkt(pA0, pA1, K_lds, qr, r32, hi); partialSM(pA0, pA1, m_reg, mnA, alA);
.LBB0_329:
	s_and_b64 vcc, exec, s[10:11]
	s_cbranch_vccz .LBB0_767
	v_mbcnt_lo_u32_b32 v2, -1, 0
	v_mbcnt_hi_u32_b32 v2, -1, v2
	s_movk_i32 s4, 0xffe0
	v_add_u32_e32 v3, s69, v2
	v_ashrrev_i32_e32 v4, 1, v3
	v_bfi_b32 v5, s4, v4, v2
	v_readlane_b32 s4, v255, 0
	v_readlane_b32 s5, v255, 1
	v_bfe_u32 v186, v2, 5, 1
	v_lshlrev_b32_e32 v160, 4, v186
	v_mov_b64_e32 v[0:1], s[4:5]
	v_mad_i64_i32 v[0:1], s[4:5], v5, s56, v[0:1]
	v_lshl_add_u64 v[0:1], v[0:1], 0, v[160:161]
	s_mov_b32 s4, 0x2aaaaaab
	flat_load_dwordx4 v[140:143], v[0:1]
	flat_load_dwordx4 v[136:139], v[0:1] offset:32
	flat_load_dwordx4 v[132:135], v[0:1] offset:64
	flat_load_dwordx4 v[128:131], v[0:1] offset:96
	flat_load_dwordx4 v[124:127], v[0:1] offset:128
	flat_load_dwordx4 v[120:123], v[0:1] offset:160
	flat_load_dwordx4 v[116:119], v[0:1] offset:192
	flat_load_dwordx4 v[112:115], v[0:1] offset:224
	flat_load_dwordx4 v[108:111], v[0:1] offset:256
	flat_load_dwordx4 v[104:107], v[0:1] offset:288
	flat_load_dwordx4 v[100:103], v[0:1] offset:320
	flat_load_dwordx4 v[96:99], v[0:1] offset:352
	v_mul_hi_i32 v1, v3, s4
	v_lshrrev_b32_e32 v5, 31, v1
	v_ashrrev_i32_e32 v1, 2, v1
	v_add_u32_e32 v1, v1, v5
	v_lshlrev_b32_e32 v0, 4, v3
	v_mul_lo_u32 v5, v1, s56
	v_lshlrev_b32_e32 v1, 3, v1
	v_sub_u32_e32 v6, v0, v5
	v_and_b32_e32 v1, 0x70, v1
	v_xad_u32 v48, v6, v1, v5
	v_add_u32_e32 v1, 0x2000, v0
	v_mul_hi_i32 v5, v1, s4
	v_lshrrev_b32_e32 v6, 31, v5
	v_ashrrev_i32_e32 v5, 6, v5
	v_add_u32_e32 v5, v5, v6
	v_mul_i32_i24_e32 v6, 0x180, v5
	v_lshlrev_b32_e32 v5, 3, v5
	v_sub_u32_e32 v7, v1, v6
	v_and_b32_e32 v5, 0x70, v5
	v_xad_u32 v50, v7, v5, v6
	v_add_u32_e32 v5, 0x4000, v0
	v_mul_hi_i32 v6, v5, s4
	v_lshrrev_b32_e32 v7, 31, v6
	v_ashrrev_i32_e32 v6, 6, v6
	v_add_u32_e32 v6, v6, v7
	v_mul_i32_i24_e32 v7, 0x180, v6
	v_lshlrev_b32_e32 v6, 3, v6
	v_sub_u32_e32 v5, v5, v7
	v_and_b32_e32 v6, 0x70, v6
	v_xad_u32 v52, v5, v6, v7
	v_ashrrev_i32_e32 v5, 4, v3
	v_ashrrev_i32_e32 v1, 8, v1
	v_and_b32_e32 v63, -16, v5
	v_lshrrev_b32_e32 v6, 1, v3
	v_lshrrev_b32_e32 v5, 1, v5
	v_lshrrev_b32_e32 v7, 1, v1
	v_and_b32_e32 v64, 8, v6
	v_and_b32_e32 v65, 4, v5
	v_lshlrev_b32_e32 v6, 1, v3
	v_and_b32_e32 v7, 4, v7
	v_bfe_u32 v62, v3, 2, 2
	v_or_b32_e32 v5, v65, v63
	v_and_b32_e32 v66, 0xc0, v6
	v_and_b32_e32 v67, 48, v0
	v_and_or_b32 v68, v1, -16, v7
	v_or3_b32 v5, v5, v62, v64
	v_or_b32_e32 v6, v67, v66
	v_or3_b32 v1, v68, v62, v64
	v_add_u32_e32 v192, 0, v0
	v_lshl_or_b32 v5, v5, 8, v6
	v_lshl_or_b32 v1, v1, 8, v6
	v_add_u32_e32 v6, 0xc000, v192
	s_add_i32 s6, 0, 0x1e000
	v_readfirstlane_b32 s5, v6
	v_add_u32_e32 v6, 0xe000, v192
	s_mov_b32 m0, s5
	v_readfirstlane_b32 s5, v6
	v_add_u32_e32 v6, 0x10000, v192
	global_load_lds_dwordx4 v48, s[86:87]
	s_mov_b32 m0, s5
	v_readfirstlane_b32 s5, v6
	global_load_lds_dwordx4 v50, s[86:87]
	s_mov_b32 m0, s5
	v_readfirstlane_b32 s5, v192
	v_add_u32_e32 v6, 0x2000, v192
	s_cmp_lg_u32 0, -1
	global_load_lds_dwordx4 v52, s[86:87]
	s_mov_b32 m0, s5
	v_readfirstlane_b32 s5, v6
	s_cselect_b32 s4, 0, 0
	global_load_lds_dwordx4 v5, s[28:29]
	s_mov_b32 m0, s5
	s_add_i32 s5, 0, 0x12000
	v_add_u32_e32 v6, s5, v0
	v_add_u32_e32 v7, 0x2000, v6
	v_readfirstlane_b32 s5, v6
	global_load_lds_dwordx4 v1, s[28:29]
	s_mov_b32 m0, s5
	v_readfirstlane_b32 s5, v7
	v_add_u32_e32 v6, 0x4000, v6
	global_load_lds_dwordx4 v48, s[54:55]
	s_mov_b32 m0, s5
	v_readfirstlane_b32 s5, v6
	global_load_lds_dwordx4 v50, s[54:55]
	s_mov_b32 m0, s5
	v_and_b32_e32 v69, 63, v2
	global_load_lds_dwordx4 v52, s[54:55]
	v_and_b32_e32 v3, 0x3fffffc0, v3
	v_and_b32_e32 v164, 0xffffffe0, v4
	v_lshlrev_b32_e32 v4, 4, v2
	v_lshl_add_u32 v165, v3, 2, s6
	v_lshlrev_b32_e32 v3, 3, v69
	v_and_b32_e32 v4, 0xc0, v4
	v_lshlrev_b32_e32 v6, 1, v2
	v_and_or_b32 v4, v3, 24, v4
	v_and_b32_e32 v6, 32, v6
	v_and_b32_e32 v3, 0x100, v3
	s_waitcnt vmcnt(5) lgkmcnt(0)
	v_or3_b32 v3, v4, v6, v3
	v_and_b32_e32 v187, 31, v2
	s_mov_b32 s31, 1
	s_mov_b32 s30, 4
	s_mov_b32 s12, 0
	v_add_u32_e32 v190, s4, v3
	v_mov_b32_e32 v49, v161
	v_mov_b32_e32 v51, v161
	v_mov_b32_e32 v53, v161
	s_barrier
	v_add_u32_e32 v0, s83, v0
	v_add_u32_e32 v3, 0x2000, v0
	v_readfirstlane_b32 s4, v0
	s_mov_b32 m0, s4
	v_readfirstlane_b32 s4, v3
	v_add_u32_e32 v0, 0x4000, v0
	global_load_lds_dwordx4 v48, s[44:45]
	s_mov_b32 m0, s4
	v_readfirstlane_b32 s4, v0
	v_add_u32_e32 v0, 0x4000, v192
	global_load_lds_dwordx4 v50, s[44:45]
	s_mov_b32 m0, s4
	v_readfirstlane_b32 s4, v0
	v_add_u32_e32 v0, 0x6000, v192
	global_load_lds_dwordx4 v52, s[44:45]
	s_mov_b32 m0, s4
	v_readfirstlane_b32 s4, v0
	v_lshlrev_b32_e32 v0, 3, v2
	v_mul_u32_u24_e32 v8, 0x180, v187
	v_and_b32_e32 v9, 0x70, v0
	global_load_lds_dwordx4 v5, s[50:51]
	s_mov_b32 m0, s4
	v_bitop3_b32 v193, v160, v8, v9 bitop3:0xde
	global_load_lds_dwordx4 v1, s[50:51]
	v_add_u32_e32 v4, 0, v193
	ds_read_b128 v[0:3], v4 offset:49152
	ds_read_b128 v[4:7], v4 offset:61440
	s_waitcnt vmcnt(0) lgkmcnt(0)
	v_mfma_f32_32x32x16_bf16 v[16:31], v[0:3], v[140:143], 0
	v_or_b32_e32 v0, 32, v160
	v_bitop3_b32 v199, v0, v8, v9 bitop3:0xde
	s_mov_b32 s13, s12
	s_mov_b32 s14, s12
	s_mov_b32 s15, s12
	s_mov_b32 s16, s12
	s_mov_b32 s17, s12
	v_mfma_f32_32x32x16_bf16 v[32:47], v[4:7], v[140:143], 0
	v_add_u32_e32 v4, 0, v199
	ds_read_b128 v[0:3], v4 offset:49152
	ds_read_b128 v[4:7], v4 offset:61440
	s_mov_b32 s18, s12
	s_mov_b32 s19, s12
	s_mov_b32 s20, s12
	s_mov_b32 s21, s12
	s_mov_b32 s22, s12
	s_waitcnt lgkmcnt(1)
	v_mfma_f32_32x32x16_bf16 v[16:31], v[0:3], v[136:139], v[16:31]
	v_or_b32_e32 v0, 64, v160
	v_bitop3_b32 v200, v0, v8, v9 bitop3:0xde
	s_mov_b32 s23, s12
	s_mov_b32 s24, s12
	s_mov_b32 s25, s12
	s_mov_b32 s26, s12
	s_mov_b32 s27, s12
	s_waitcnt lgkmcnt(0)
; __device__ __forceinline__ void partialSM(f32x16& p0, f32x16& p1, float& m_reg, float& mn, float& alpha) {
;   constexpr float C = ASCALE * 1.4426950408889634f;
;   float pmax = p0[0]; for (int r = 1; r < 16; ++r) pmax = fmaxf(pmax, p0[r]); for (int r = 0; r < 16; ++r) pmax = fmaxf(pmax, p1[r]);
;   { auto rr = __builtin_amdgcn_permlane32_swap(__float_as_uint(pmax), __float_as_uint(pmax), false, false);
;     pmax = fmaxf(__uint_as_float(rr[0]), __uint_as_float(rr[1])); }
;   if (__builtin_expect(__all(pmax - m_reg <= THR / ASCALE), 1)) { mn = m_reg; alpha = 1.f; }
;   else { mn = fmaxf(m_reg, pmax); alpha = __builtin_amdgcn_exp2f((m_reg - mn) * C); m_reg = mn; }
;   float mnC = -mn * C;
;   for (int r = 0; r < 16; ++r) p0[r] = fmaf(p0[r], C, mnC); for (int r = 0; r < 16; ++r) p1[r] = fmaf(p1[r], C, mnC);
;   for (int r = 0; r < 16; ++r) p0[r] = __builtin_amdgcn_exp2f(p0[r]);
; }
; __device__ __forceinline__ void finishSM(f32x16& p0, f32x16& p1, float alpha, float& l_reg, bf16x8& pa0, bf16x8& pa1, bf16x8& pa2, bf16x8& pa3) {
;   for (int r = 0; r < 16; ++r) p1[r] = __builtin_amdgcn_exp2f(p1[r]);
;   float ps = 0; for (int r = 0; r < 16; ++r) ps += p0[r]; for (int r = 0; r < 16; ++r) ps += p1[r];
;   { auto rr = __builtin_amdgcn_permlane32_swap(__float_as_uint(ps), __float_as_uint(ps), false, false);
;     ps = __uint_as_float(rr[0]) + __uint_as_float(rr[1]); }
;   l_reg = l_reg * alpha + ps;
;     ...
;   PK4(p0, 0, pa0); PK4(p0, 8, pa1); PK4(p1, 0, pa2); PK4(p1, 8, pa3);
;     ...
; }
; __device__ __forceinline__ void qkt(f32x16& p0, f32x16& p1, const char* Ks, const bf16x8* qr, int r32, int hi) {
;   p0 = f32x16{}; p1 = f32x16{};
; #pragma unroll
;   for (int d0 = 0; d0 < 12; ++d0) { int cb = (d0 * 16 + hi * 8) * 2;
;     bf16x8 b0 = *reinterpret_cast<const bf16x8*>(Ks + KSWZ(r32, cb));
;     bf16x8 b1 = *reinterpret_cast<const bf16x8*>(Ks + KSWZ(32 + r32, cb));
;     p0 = __builtin_amdgcn_mfma_f32_32x32x16_bf16(b0, qr[d0], p0, 0, 0, 0);
;     p1 = __builtin_amdgcn_mfma_f32_32x32x16_bf16(b1, qr[d0], p1, 0, 0, 0); }
; }
	v_mfma_f32_32x32x16_bf16 v[32:47], v[4:7], v[136:139], v[32:47]
	v_add_u32_e32 v4, 0, v200
	ds_read_b128 v[0:3], v4 offset:49152
	ds_read_b128 v[4:7], v4 offset:61440
	v_mov_b32_e32 v168, v52
	v_mov_b32_e32 v167, v50
	v_mov_b32_e32 v166, v48
	s_add_u32 s98, s80, s48
	s_addc_u32 s99, s81, s49
	s_add_u32 s98, s98, s70
	s_addc_u32 s99, s99, s71
	v_cmp_gt_u32_e64 s[6:7], 32, v69
	v_lshl_add_u32 v188, v187, 2, v165
	s_waitcnt lgkmcnt(1)
	v_mfma_f32_32x32x16_bf16 v[16:31], v[0:3], v[132:135], v[16:31]
	v_or_b32_e32 v0, 0x60, v160
	v_bitop3_b32 v202, v0, v8, v9 bitop3:0xde
	v_mov_b32_e32 v189, 0
	s_waitcnt lgkmcnt(0)
	v_mfma_f32_32x32x16_bf16 v[32:47], v[4:7], v[132:135], v[32:47]
	v_add_u32_e32 v4, 0, v202
	ds_read_b128 v[0:3], v4 offset:49152
	ds_read_b128 v[4:7], v4 offset:61440
	s_waitcnt lgkmcnt(1)
	v_mfma_f32_32x32x16_bf16 v[16:31], v[0:3], v[128:131], v[16:31]
	v_or_b32_e32 v0, 0x80, v160
	v_xad_u32 v207, v0, v9, v8
	v_add_u32_e32 v10, 0, v207
	s_waitcnt lgkmcnt(0)
	v_mfma_f32_32x32x16_bf16 v[32:47], v[4:7], v[128:131], v[32:47]
	ds_read_b128 v[0:3], v10 offset:49152
	ds_read_b128 v[4:7], v10 offset:61440
	s_waitcnt lgkmcnt(1)
	v_mfma_f32_32x32x16_bf16 v[16:31], v[0:3], v[124:127], v[16:31]
	v_or_b32_e32 v0, 0xa0, v160
	v_xad_u32 v203, v0, v9, v8
	v_add_u32_e32 v10, 0, v203
	s_waitcnt lgkmcnt(0)
	v_mfma_f32_32x32x16_bf16 v[32:47], v[4:7], v[124:127], v[32:47]
	ds_read_b128 v[0:3], v10 offset:49152
	ds_read_b128 v[4:7], v10 offset:61440
	s_waitcnt lgkmcnt(1)
	v_mfma_f32_32x32x16_bf16 v[16:31], v[0:3], v[120:123], v[16:31]
	v_or_b32_e32 v0, 0xc0, v160
	v_xad_u32 v201, v0, v9, v8
	v_add_u32_e32 v10, 0, v201
	s_waitcnt lgkmcnt(0)
	v_mfma_f32_32x32x16_bf16 v[32:47], v[4:7], v[120:123], v[32:47]
	ds_read_b128 v[0:3], v10 offset:49152
	ds_read_b128 v[4:7], v10 offset:61440
	s_waitcnt lgkmcnt(1)
	v_mfma_f32_32x32x16_bf16 v[16:31], v[0:3], v[116:119], v[16:31]
	v_or_b32_e32 v0, 0xe0, v160
	v_xad_u32 v198, v0, v9, v8
	v_add_u32_e32 v10, 0, v198
	s_waitcnt lgkmcnt(0)
	v_mfma_f32_32x32x16_bf16 v[32:47], v[4:7], v[116:119], v[32:47]
	ds_read_b128 v[0:3], v10 offset:49152
	ds_read_b128 v[4:7], v10 offset:61440
	s_waitcnt lgkmcnt(1)
	v_mfma_f32_32x32x16_bf16 v[16:31], v[0:3], v[112:115], v[16:31]
	v_or_b32_e32 v0, 0x100, v160
	v_xad_u32 v197, v0, v9, v8
	v_add_u32_e32 v10, 0, v197
	s_waitcnt lgkmcnt(0)
	v_mfma_f32_32x32x16_bf16 v[32:47], v[4:7], v[112:115], v[32:47]
	ds_read_b128 v[0:3], v10 offset:49152
	ds_read_b128 v[4:7], v10 offset:61440
	s_waitcnt lgkmcnt(1)
	v_mfma_f32_32x32x16_bf16 v[16:31], v[0:3], v[108:111], v[16:31]
	v_or_b32_e32 v0, 0x120, v160
	v_xad_u32 v196, v0, v9, v8
	v_add_u32_e32 v10, 0, v196
	ds_read_b128 v[0:3], v10 offset:49152
	s_waitcnt lgkmcnt(1)
	v_mfma_f32_32x32x16_bf16 v[32:47], v[4:7], v[108:111], v[32:47]
	ds_read_b128 v[4:7], v10 offset:61440
	s_waitcnt lgkmcnt(1)
	v_mfma_f32_32x32x16_bf16 v[16:31], v[0:3], v[104:107], v[16:31]
	v_or_b32_e32 v0, 0x140, v160
	v_xad_u32 v195, v0, v9, v8
	v_add_u32_e32 v10, 0, v195
	ds_read_b128 v[0:3], v10 offset:49152
	ds_read_b128 v[54:57], v10 offset:61440
	s_waitcnt lgkmcnt(2)
	v_mfma_f32_32x32x16_bf16 v[32:47], v[4:7], v[104:107], v[32:47]
	v_or_b32_e32 v4, 0x160, v160
	v_xad_u32 v194, v4, v9, v8
	v_add_u32_e32 v8, 0, v194
	ds_read_b128 v[4:7], v8 offset:49152
	ds_read_b128 v[58:61], v8 offset:61440
	s_waitcnt lgkmcnt(3)
	v_mfma_f32_32x32x16_bf16 v[16:31], v[0:3], v[100:103], v[16:31]
	s_waitcnt lgkmcnt(1)
	v_mfma_f32_32x32x16_bf16 v[16:31], v[4:7], v[96:99], v[16:31]
	v_mov_b64_e32 v[0:1], s[12:13]
	v_mov_b64_e32 v[14:15], s[26:27]
	v_mov_b64_e32 v[2:3], s[14:15]
	v_mov_b64_e32 v[4:5], s[16:17]
	v_mov_b64_e32 v[6:7], s[18:19]
	v_mov_b64_e32 v[8:9], s[20:21]
	v_mov_b64_e32 v[10:11], s[22:23]
	v_mfma_f32_32x32x16_bf16 v[32:47], v[54:57], v[100:103], v[32:47]
	s_nop 3
	v_max_f32_e32 v70, v17, v17
	v_max_f32_e32 v71, v16, v16
	v_max_f32_e32 v70, v71, v70
	v_max3_f32 v54, v70, v18, v19
	v_max3_f32 v54, v54, v20, v21
	v_max3_f32 v54, v54, v22, v23
	v_max3_f32 v54, v54, v24, v25
	s_waitcnt lgkmcnt(0)
	v_mfma_f32_32x32x16_bf16 v[32:47], v[58:61], v[96:99], v[32:47]
	v_max3_f32 v54, v54, v26, v27
	v_max3_f32 v54, v54, v28, v29
	v_max3_f32 v54, v54, v30, v31
	v_mov_b64_e32 v[12:13], s[24:25]
	s_nop 7
	v_max3_f32 v54, v54, v32, v33
	v_max3_f32 v54, v54, v34, v35
	v_max3_f32 v54, v54, v36, v37
	v_max3_f32 v54, v54, v38, v39
	v_max3_f32 v54, v54, v40, v41
	v_max3_f32 v54, v54, v42, v43
	v_max3_f32 v54, v54, v44, v45
	v_max3_f32 v54, v54, v46, v47
	v_mov_b32_e32 v55, v54
	s_nop 1
	v_permlane32_swap_b32_e32 v54, v55
	v_max_f32_e32 v55, v55, v55
	v_max_f32_e32 v54, v54, v54
	v_max_f32_e32 v54, v54, v55
	v_add_f32_e32 v55, 0x7149f2ca, v54
	v_cmp_ge_f32_e32 vcc, s35, v55
	s_cmp_eq_u64 vcc, exec
	v_max_f32_e32 v54, 0xf149f2ca, v54
	s_cselect_b64 vcc, -1, 0
	v_mov_b32_e32 v55, 0xf149f2ca
	v_cndmask_b32_e32 v191, v54, v55, vcc
	v_sub_f32_e32 v56, 0xf149f2ca, v54
	v_mul_f32_e32 v54, 0xbdd53b94, v191
	v_fmamk_f32 v16, v16, 0x3dd53b94, v54
	v_exp_f32_e32 v218, v16
	v_fmamk_f32 v16, v17, 0x3dd53b94, v54
	v_exp_f32_e32 v220, v16
	v_fmamk_f32 v16, v18, 0x3dd53b94, v54
	v_exp_f32_e32 v221, v16
	v_fmamk_f32 v16, v19, 0x3dd53b94, v54
	v_exp_f32_e32 v222, v16
	v_fmamk_f32 v16, v20, 0x3dd53b94, v54
	v_exp_f32_e32 v223, v16
	v_fmamk_f32 v16, v21, 0x3dd53b94, v54
	v_exp_f32_e32 v225, v16
	v_fmamk_f32 v16, v22, 0x3dd53b94, v54
	v_exp_f32_e32 v224, v16
	v_fmamk_f32 v16, v23, 0x3dd53b94, v54
	v_exp_f32_e32 v226, v16
	v_fmamk_f32 v16, v24, 0x3dd53b94, v54
	v_exp_f32_e32 v211, v16
	v_fmamk_f32 v16, v25, 0x3dd53b94, v54
	v_exp_f32_e32 v212, v16
	v_fmamk_f32 v16, v26, 0x3dd53b94, v54
	v_exp_f32_e32 v213, v16
; #define ISSUE_K(t, slot) do { const char* kg_ = (const char*)(Kh + (long)(t) * (KVBLK * 192)); char* kl_ = K_lds + (slot) * SHM_K + tid * 16; \
;     DMA16(kg_ + kso0, kl_); DMA16(kg_ + kso1, kl_ + 8192); DMA16(kg_ + kso2, kl_ + 16384); } while (0)
; #define ISSUE_V(t, slot) do { const char* vg_ = (const char*)(Vh + (long)(t) * (KVBLK * 128)); char* vl_ = V_lds + (slot) * SHM_V + tid * 16; \
;     DMA16(vg_ + vso0, vl_); DMA16(vg_ + vso1, vl_ + 8192); } while (0)
; #define TBAR(n) do { asm volatile("s_waitcnt vmcnt(" #n ") lgkmcnt(0)" ::: "memory"); __builtin_amdgcn_s_barrier(); SBAR(); } while (0)
; __device__ __forceinline__ void qkt(f32x16& p0, f32x16& p1, const char* Ks, const bf16x8* qr, int r32, int hi) {
;   p0 = f32x16{}; p1 = f32x16{};
; #pragma unroll
;   for (int d0 = 0; d0 < 12; ++d0) { int cb = (d0 * 16 + hi * 8) * 2;
;     bf16x8 b0 = *reinterpret_cast<const bf16x8*>(Ks + KSWZ(r32, cb));
;     bf16x8 b1 = *reinterpret_cast<const bf16x8*>(Ks + KSWZ(32 + r32, cb));
;     p0 = __builtin_amdgcn_mfma_f32_32x32x16_bf16(b0, qr[d0], p0, 0, 0, 0);
;     p1 = __builtin_amdgcn_mfma_f32_32x32x16_bf16(b1, qr[d0], p1, 0, 0, 0); }
; }
; __device__ __forceinline__ void attn_body(const u16* __restrict__ Qb, const u16* __restrict__ Kh, const u16* __restrict__ Vh,
;                                           u16* __restrict__ Ob, int seq, int wvs) {
;     ...
;   f32x16 pA0, pA1, pB0, pB1; float mnA, mnB, alA, alB; bf16x8 pa0, pa1, pa2, pa3; const int NT = seq / KVBLK;
;   ISSUE_K(0, 0); ISSUE_V(0, 0); ISSUE_K(1, 1);
;   TBAR(5);
;   ISSUE_K(2, 2); ISSUE_V(1, 1);
;   qkt(pA0, pA1, K_lds, qr, r32, hi); partialSM(pA0, pA1, m_reg, mnA, alA);
;   int sK = 1, sV = 0;
;   for (int j = 1; j + 1 < NT; j += 2) {
;     TBAR(5);
;     ISSUE_K(j + 2, NEXT3(NEXT3(sK))); ISSUE_V(j + 1, NEXT3(NEXT3(sV)));
;     qkt(pB0, pB1, K_lds + sK * SHM_K, qr, r32, hi);
	v_fmamk_f32 v16, v27, 0x3dd53b94, v54
	v_exp_f32_e32 v215, v16
	v_fmamk_f32 v16, v28, 0x3dd53b94, v54
	v_exp_f32_e32 v214, v16
	v_fmamk_f32 v16, v29, 0x3dd53b94, v54
	v_exp_f32_e32 v216, v16
	v_fmamk_f32 v16, v30, 0x3dd53b94, v54
	v_exp_f32_e32 v217, v16
	v_or3_b32 v16, v68, v64, v62
	v_lshlrev_b32_e32 v16, 8, v16
	v_mul_f32_e32 v56, 0x3dd53b94, v56
	v_or3_b32 v16, v16, v66, v67
	v_mov_b32_e32 v17, v161
	v_exp_f32_e32 v56, v56
	v_mov_b32_e32 v170, v16
	s_add_u32 s100, s80, s88
	s_addc_u32 s101, s81, s89
	s_add_u32 s100, s100, s72
	s_addc_u32 s101, s101, s73
	v_or_b32_e32 v16, v63, v64
	v_pk_fma_f32 v[144:145], v[46:47], s[68:69], v[54:55] op_sel_hi:[1,0,0]
	v_pk_fma_f32 v[146:147], v[44:45], s[68:69], v[54:55] op_sel_hi:[1,0,0]
	v_pk_fma_f32 v[148:149], v[42:43], s[68:69], v[54:55] op_sel_hi:[1,0,0]
	v_pk_fma_f32 v[150:151], v[40:41], s[68:69], v[54:55] op_sel_hi:[1,0,0]
	v_pk_fma_f32 v[152:153], v[38:39], s[68:69], v[54:55] op_sel_hi:[1,0,0]
	v_pk_fma_f32 v[154:155], v[36:37], s[68:69], v[54:55] op_sel_hi:[1,0,0]
	v_pk_fma_f32 v[156:157], v[34:35], s[68:69], v[54:55] op_sel_hi:[1,0,0]
	v_pk_fma_f32 v[158:159], v[32:33], s[68:69], v[54:55] op_sel_hi:[1,0,0]
	v_fmac_f32_e32 v54, 0x3dd53b94, v31
	v_or3_b32 v16, v16, v65, v62
	v_exp_f32_e32 v219, v54
	v_lshlrev_b32_e32 v16, 8, v16
	v_or3_b32 v16, v16, v66, v67
	v_cndmask_b32_e64 v208, v56, 1.0, vcc
	v_mov_b32_e32 v169, v16
	v_mov_b64_e32 v[62:63], v[14:15]
	v_mov_b64_e32 v[46:47], v[14:15]
	v_mov_b64_e32 v[30:31], v[14:15]
	v_mov_b64_e32 v[60:61], v[12:13]
	v_mov_b64_e32 v[58:59], v[10:11]
	v_mov_b64_e32 v[56:57], v[8:9]
	v_mov_b64_e32 v[54:55], v[6:7]
	v_mov_b64_e32 v[52:53], v[4:5]
	v_mov_b64_e32 v[50:51], v[2:3]
	v_mov_b64_e32 v[48:49], v[0:1]
	v_mov_b64_e32 v[44:45], v[12:13]
	v_mov_b64_e32 v[42:43], v[10:11]
	v_mov_b64_e32 v[40:41], v[8:9]
	v_mov_b64_e32 v[38:39], v[6:7]
	v_mov_b64_e32 v[36:37], v[4:5]
	v_mov_b64_e32 v[34:35], v[2:3]
	v_mov_b64_e32 v[32:33], v[0:1]
	v_mov_b64_e32 v[28:29], v[12:13]
	v_mov_b64_e32 v[26:27], v[10:11]
	v_mov_b64_e32 v[24:25], v[8:9]
	v_mov_b64_e32 v[22:23], v[6:7]
	v_mov_b64_e32 v[20:21], v[4:5]
	v_mov_b64_e32 v[18:19], v[2:3]
	v_mov_b64_e32 v[16:17], v[0:1]
.LBB0_331:
	s_waitcnt vmcnt(5) lgkmcnt(0)
	s_barrier
	s_add_i32 s4, s31, 1
	s_cmp_lg_u32 s31, 2
	s_cselect_b32 s13, s4, 0
	s_mul_i32 s15, s13, 0x6000
	s_add_i32 s10, s15, 0x6000
	s_cmp_eq_u32 s13, 2
	s_cselect_b64 s[4:5], -1, 0
	s_and_b64 s[8:9], s[4:5], exec
	s_cselect_b32 s8, 0, s10
	s_lshl_b32 vcc_lo, s69, 4
	s_add_i32 vcc_lo, vcc_lo, s8
	s_add_i32 vcc_hi, vcc_lo, 0xc000
	s_mov_b32 m0, vcc_hi
	s_add_i32 vcc_hi, vcc_lo, 0xe000
	global_load_lds_dwordx4 v166, s[98:99]
	s_mov_b32 m0, vcc_hi
	s_add_i32 vcc_hi, vcc_lo, 0x10000
	global_load_lds_dwordx4 v167, s[98:99]
	s_mov_b32 m0, vcc_hi
	s_add_i32 s8, s12, 1
	s_cmp_lg_u32 s12, 2
	s_cselect_b32 s16, s8, 0
	s_lshl_b32 s14, s16, 14
	s_add_i32 s17, s14, 0x4000
	s_cmp_eq_u32 s16, 2
	s_cselect_b64 s[8:9], -1, 0
	s_and_b64 s[10:11], s[8:9], exec
	s_cselect_b32 s10, 0, s17
	global_load_lds_dwordx4 v168, s[98:99]
	s_lshl_b32 vcc_lo, s69, 4
	s_add_i32 vcc_lo, vcc_lo, s10
	s_mov_b32 m0, vcc_lo
	s_add_i32 vcc_hi, vcc_lo, 0x2000
	global_load_lds_dwordx4 v169, s[100:101]
	s_mov_b32 m0, vcc_hi
	s_add_u32 s98, s98, 0x6000
	s_addc_u32 s99, s99, 0
	global_load_lds_dwordx4 v170, s[100:101]
	s_add_u32 s100, s100, 0x4000
	s_addc_u32 s101, s101, 0
	s_mul_i32 s10, s31, 0x6000
	s_add_i32 s10, s10, 0
	v_add_u32_e32 v162, s10, v193
	v_add_u32_e32 v253, s10, v199
	v_add_u32_e32 v252, s10, v200
	v_add_u32_e32 v244, s10, v202
	ds_read_b128 v[64:67], v162 offset:49152
	ds_read_b128 v[68:71], v162 offset:61440
	ds_read_b128 v[228:231], v253 offset:49152
	ds_read_b128 v[232:235], v253 offset:61440
	s_waitcnt lgkmcnt(2)
	v_mfma_f32_32x32x16_bf16 v[80:95], v[64:67], v[140:143], 0
	ds_read_b128 v[236:239], v252 offset:49152
	ds_read_b128 v[240:243], v252 offset:61440
	v_exp_f32_e32 v158, v158
	v_exp_f32_e32 v159, v159
	v_exp_f32_e32 v156, v156
	v_exp_f32_e32 v157, v157
	v_mfma_f32_32x32x16_bf16 v[64:79], v[68:71], v[140:143], 0
	v_exp_f32_e32 v154, v154
	v_exp_f32_e32 v155, v155
	v_exp_f32_e32 v163, v153
	v_exp_f32_e32 v206, v150
	v_exp_f32_e32 v227, v151
	v_cvt_pk_bf16_f32 v150, v214, v216
	v_cvt_pk_bf16_f32 v151, v217, v219
	s_waitcnt lgkmcnt(2)
	v_mfma_f32_32x32x16_bf16 v[64:79], v[232:235], v[136:139], v[64:79]
	v_cvt_pk_bf16_f32 v153, v156, v157
	v_mfma_f32_32x32x16_bf16 v[80:95], v[228:231], v[136:139], v[80:95]
	ds_read_b128 v[228:231], v244 offset:49152
	ds_read_b128 v[232:235], v244 offset:61440
	s_waitcnt lgkmcnt(2)
	v_mfma_f32_32x32x16_bf16 v[64:79], v[240:243], v[132:135], v[64:79]
	v_mfma_f32_32x32x16_bf16 v[80:95], v[236:239], v[132:135], v[80:95]
	ds_read_b128 v[236:239], v162 offset:49280
	ds_read_b128 v[240:243], v162 offset:61568
	s_waitcnt lgkmcnt(2)
	v_mfma_f32_32x32x16_bf16 v[64:79], v[232:235], v[128:131], v[64:79]
	v_mfma_f32_32x32x16_bf16 v[80:95], v[228:231], v[128:131], v[80:95]
	ds_read_b128 v[228:231], v253 offset:49280
	ds_read_b128 v[232:235], v253 offset:61568
	s_waitcnt lgkmcnt(2)
	v_mfma_f32_32x32x16_bf16 v[64:79], v[240:243], v[124:127], v[64:79]
	v_mfma_f32_32x32x16_bf16 v[80:95], v[236:239], v[124:127], v[80:95]
	ds_read_b128 v[236:239], v252 offset:49280
	ds_read_b128 v[240:243], v252 offset:61568
	s_waitcnt lgkmcnt(2)
	v_mfma_f32_32x32x16_bf16 v[64:79], v[232:235], v[120:123], v[64:79]
	v_mfma_f32_32x32x16_bf16 v[80:95], v[228:231], v[120:123], v[80:95]
	ds_read_b128 v[228:231], v244 offset:49280
	ds_read_b128 v[232:235], v244 offset:61568
	s_waitcnt lgkmcnt(2)
; __device__ __forceinline__ void finishSM(f32x16& p0, f32x16& p1, float alpha, float& l_reg, bf16x8& pa0, bf16x8& pa1, bf16x8& pa2, bf16x8& pa3) {
;   for (int r = 0; r < 16; ++r) p1[r] = __builtin_amdgcn_exp2f(p1[r]);
;   float ps = 0; for (int r = 0; r < 16; ++r) ps += p0[r]; for (int r = 0; r < 16; ++r) ps += p1[r];
;   { auto rr = __builtin_amdgcn_permlane32_swap(__float_as_uint(ps), __float_as_uint(ps), false, false);
;     ps = __uint_as_float(rr[0]) + __uint_as_float(rr[1]); }
;   l_reg = l_reg * alpha + ps;
;     ...
;   PK4(p0, 0, pa0); PK4(p0, 8, pa1); PK4(p1, 0, pa2); PK4(p1, 8, pa3);
;     ...
; }
; __device__ __forceinline__ void qkt(f32x16& p0, f32x16& p1, const char* Ks, const bf16x8* qr, int r32, int hi) {
;   p0 = f32x16{}; p1 = f32x16{};
; #pragma unroll
;   for (int d0 = 0; d0 < 12; ++d0) { int cb = (d0 * 16 + hi * 8) * 2;
;     bf16x8 b0 = *reinterpret_cast<const bf16x8*>(Ks + KSWZ(r32, cb));
;     bf16x8 b1 = *reinterpret_cast<const bf16x8*>(Ks + KSWZ(32 + r32, cb));
;     p0 = __builtin_amdgcn_mfma_f32_32x32x16_bf16(b0, qr[d0], p0, 0, 0, 0);
;     p1 = __builtin_amdgcn_mfma_f32_32x32x16_bf16(b1, qr[d0], p1, 0, 0, 0); }
; }
; __device__ __forceinline__ int v_st(int k, int c) { const int kk = (k & ~0xC) | ((k & 4) << 1) | ((k & 8) >> 1); return ((kk >> 3) * 4 + (c >> 5)) * 512 + ((kk & 7) * 32 + (c & 31)) * 2; }
; __device__ __forceinline__ int v_rd_base(int lane) { return ((lane & 3) << 3) | (((lane >> 2) & 3) << 6) | (((lane >> 4) & 1) << 5) | (((lane >> 5) & 1) << 8); }
; template <int OFF> __device__ __forceinline__ s16x4 tr_read(int vb) {
;   return __builtin_amdgcn_ds_read_tr16_b64_v4i16((lds_s16x4*)(uintptr_t)(unsigned)(vb + OFF));
; }
; template <int D0> __device__ __forceinline__ void pv_one(f32x16& od, int vb, bf16x8 pa0, bf16x8 pa1, bf16x8 pa2, bf16x8 pa3) {
;   const s16x4 l0 = tr_read<v_rd_off(D0, 0, 0)>(vb), h0 = tr_read<v_rd_off(D0, 0, 1)>(vb), l1 = tr_read<v_rd_off(D0, 1, 0)>(vb), h1 = tr_read<v_rd_off(D0, 1, 1)>(vb);
;   const s16x4 l2 = tr_read<v_rd_off(D0, 2, 0)>(vb), h2 = tr_read<v_rd_off(D0, 2, 1)>(vb), l3 = tr_read<v_rd_off(D0, 3, 0)>(vb), h3 = tr_read<v_rd_off(D0, 3, 1)>(vb);
;     ...
;   od = __builtin_amdgcn_mfma_f32_32x32x16_bf16(pa0, PK(l0, h0), od, 0, 0, 0);
;   od = __builtin_amdgcn_mfma_f32_32x32x16_bf16(pa1, PK(l1, h1), od, 0, 0, 0);
;   od = __builtin_amdgcn_mfma_f32_32x32x16_bf16(pa2, PK(l2, h2), od, 0, 0, 0);
	v_mfma_f32_32x32x16_bf16 v[64:79], v[240:243], v[116:119], v[64:79]
	v_mfma_f32_32x32x16_bf16 v[80:95], v[236:239], v[116:119], v[80:95]
	ds_read_b128 v[236:239], v162 offset:49408
	ds_read_b128 v[240:243], v162 offset:61696
	s_waitcnt lgkmcnt(2)
	v_mfma_f32_32x32x16_bf16 v[64:79], v[232:235], v[112:115], v[64:79]
	v_mfma_f32_32x32x16_bf16 v[80:95], v[228:231], v[112:115], v[80:95]
	ds_read_b128 v[228:231], v253 offset:49408
	ds_read_b128 v[232:235], v253 offset:61696
	s_waitcnt lgkmcnt(2)
	v_mfma_f32_32x32x16_bf16 v[64:79], v[240:243], v[108:111], v[64:79]
	v_mfma_f32_32x32x16_bf16 v[80:95], v[236:239], v[108:111], v[80:95]
	ds_read_b128 v[236:239], v252 offset:49408
	ds_read_b128 v[240:243], v252 offset:61696
	s_waitcnt lgkmcnt(2)
	v_mfma_f32_32x32x16_bf16 v[64:79], v[232:235], v[104:107], v[64:79]
	v_mfma_f32_32x32x16_bf16 v[80:95], v[228:231], v[104:107], v[80:95]
	ds_read_b128 v[228:231], v244 offset:49408
	ds_read_b128 v[232:235], v244 offset:61696
	v_lshl_add_u32 v252, s12, 14, v190
	ds_read_b64_tr_b16 v[244:245], v252
	ds_read_b64_tr_b16 v[246:247], v252 offset:2048
	ds_read_b64_tr_b16 v[248:249], v252 offset:4096
	ds_read_b64_tr_b16 v[250:251], v252 offset:6144
	v_exp_f32_e32 v162, v152
	v_cvt_pk_bf16_f32 v152, v158, v159
	s_waitcnt lgkmcnt(6)
	v_mfma_f32_32x32x16_bf16 v[64:79], v[240:243], v[100:103], v[64:79]
	v_mfma_f32_32x32x16_bf16 v[80:95], v[236:239], v[100:103], v[80:95]
	s_waitcnt lgkmcnt(4)
	v_mfma_f32_32x32x16_bf16 v[64:79], v[232:235], v[96:99], v[64:79]
	v_exp_f32_e32 v232, v144
	v_add_f32_e32 v144, 0, v218
	v_add_f32_e32 v144, v220, v144
	v_add_f32_e32 v144, v221, v144
	v_add_f32_e32 v144, v222, v144
	v_add_f32_e32 v144, v223, v144
	v_add_f32_e32 v144, v225, v144
	v_add_f32_e32 v144, v224, v144
	v_add_f32_e32 v144, v226, v144
	v_add_f32_e32 v144, v211, v144
	v_add_f32_e32 v144, v212, v144
	v_add_f32_e32 v144, v213, v144
	v_add_f32_e32 v144, v215, v144
	v_add_f32_e32 v144, v214, v144
	v_add_f32_e32 v144, v216, v144
	v_add_f32_e32 v144, v217, v144
	v_add_f32_e32 v144, v219, v144
	v_add_f32_e32 v144, v158, v144
	v_add_f32_e32 v144, v159, v144
	v_add_f32_e32 v144, v156, v144
	v_add_f32_e32 v144, v157, v144
	v_add_f32_e32 v144, v154, v144
	v_add_f32_e32 v144, v155, v144
	v_mfma_f32_32x32x16_bf16 v[80:95], v[228:231], v[96:99], v[80:95]
	v_exp_f32_e32 v228, v148
	v_add_f32_e32 v144, v162, v144
	v_exp_f32_e32 v229, v149
	v_add_f32_e32 v144, v163, v144
	v_exp_f32_e32 v230, v146
	v_add_f32_e32 v144, v206, v144
	v_exp_f32_e32 v231, v147
	v_add_f32_e32 v144, v227, v144
	v_add_f32_e32 v144, v228, v144
	v_exp_f32_e32 v233, v145
	v_add_f32_e32 v144, v229, v144
	v_add_f32_e32 v144, v230, v144
	v_add_f32_e32 v144, v231, v144
	v_add_f32_e32 v144, v232, v144
	v_add_f32_e32 v209, v233, v144
	v_cvt_pk_bf16_f32 v144, v218, v220
	v_cvt_pk_bf16_f32 v145, v221, v222
	v_cvt_pk_bf16_f32 v146, v223, v225
	v_cvt_pk_bf16_f32 v147, v224, v226
	s_nop 0
	v_permlane32_swap_b32_e32 v144, v146
	v_permlane32_swap_b32_e32 v145, v147
	v_cvt_pk_bf16_f32 v154, v154, v155
	v_cvt_pk_bf16_f32 v155, v162, v163
	v_cvt_pk_bf16_f32 v148, v211, v212
	v_cvt_pk_bf16_f32 v149, v213, v215
	v_cvt_pk_bf16_f32 v156, v206, v227
	ds_read_b64_tr_b16 v[220:221], v252 offset:8192
	ds_read_b64_tr_b16 v[222:223], v252 offset:10240
	ds_read_b64_tr_b16 v[224:225], v252 offset:12288
	ds_read_b64_tr_b16 v[226:227], v252 offset:14336
	s_waitcnt lgkmcnt(4)
; __device__ __forceinline__ void partialSM(f32x16& p0, f32x16& p1, float& m_reg, float& mn, float& alpha) {
;   constexpr float C = ASCALE * 1.4426950408889634f;
;   float pmax = p0[0]; for (int r = 1; r < 16; ++r) pmax = fmaxf(pmax, p0[r]); for (int r = 0; r < 16; ++r) pmax = fmaxf(pmax, p1[r]);
;   { auto rr = __builtin_amdgcn_permlane32_swap(__float_as_uint(pmax), __float_as_uint(pmax), false, false);
;     pmax = fmaxf(__uint_as_float(rr[0]), __uint_as_float(rr[1])); }
;   if (__builtin_expect(__all(pmax - m_reg <= THR / ASCALE), 1)) { mn = m_reg; alpha = 1.f; }
; template <int OFF> __device__ __forceinline__ s16x4 tr_read(int vb) {
;   return __builtin_amdgcn_ds_read_tr16_b64_v4i16((lds_s16x4*)(uintptr_t)(unsigned)(vb + OFF));
; }
; template <int D0> __device__ __forceinline__ void pv_one(f32x16& od, int vb, bf16x8 pa0, bf16x8 pa1, bf16x8 pa2, bf16x8 pa3) {
;   const s16x4 l0 = tr_read<v_rd_off(D0, 0, 0)>(vb), h0 = tr_read<v_rd_off(D0, 0, 1)>(vb), l1 = tr_read<v_rd_off(D0, 1, 0)>(vb), h1 = tr_read<v_rd_off(D0, 1, 1)>(vb);
;   const s16x4 l2 = tr_read<v_rd_off(D0, 2, 0)>(vb), h2 = tr_read<v_rd_off(D0, 2, 1)>(vb), l3 = tr_read<v_rd_off(D0, 3, 0)>(vb), h3 = tr_read<v_rd_off(D0, 3, 1)>(vb);
;     ...
;   od = __builtin_amdgcn_mfma_f32_32x32x16_bf16(pa0, PK(l0, h0), od, 0, 0, 0);
;   od = __builtin_amdgcn_mfma_f32_32x32x16_bf16(pa1, PK(l1, h1), od, 0, 0, 0);
;   od = __builtin_amdgcn_mfma_f32_32x32x16_bf16(pa2, PK(l2, h2), od, 0, 0, 0);
;   od = __builtin_amdgcn_mfma_f32_32x32x16_bf16(pa3, PK(l3, h3), od, 0, 0, 0);
;     ...
; }
; __device__ __forceinline__ void pv_d0(f32x16* o, int vb, bf16x8 pa0, bf16x8 pa1, bf16x8 pa2, bf16x8 pa3) {
;   pv_one<0>(o[0], vb, pa0, pa1, pa2, pa3); pv_one<1>(o[1], vb, pa0, pa1, pa2, pa3); pv_one<2>(o[2], vb, pa0, pa1, pa2, pa3); pv_one<3>(o[3], vb, pa0, pa1, pa2, pa3);
; }
	v_mfma_f32_32x32x16_bf16 v[0:15], v[144:147], v[244:247], v[0:15]
	ds_read_b64_tr_b16 v[212:213], v252 offset:512
	ds_read_b64_tr_b16 v[214:215], v252 offset:2560
	v_permlane32_swap_b32_e32 v148, v150
	v_permlane32_swap_b32_e32 v149, v151
	v_permlane32_swap_b32_e32 v152, v154
	v_permlane32_swap_b32_e32 v153, v155
	v_mfma_f32_32x32x16_bf16 v[0:15], v[148:151], v[248:251], v[0:15]
	ds_read_b64_tr_b16 v[216:217], v252 offset:4608
	ds_read_b64_tr_b16 v[218:219], v252 offset:6656
	v_cvt_pk_bf16_f32 v157, v228, v229
	v_cvt_pk_bf16_f32 v158, v230, v231
	v_cvt_pk_bf16_f32 v159, v232, v233
	s_nop 0
	v_permlane32_swap_b32_e32 v156, v158
	v_permlane32_swap_b32_e32 v157, v159
	s_waitcnt lgkmcnt(6)
	v_mfma_f32_32x32x16_bf16 v[0:15], v[152:155], v[220:223], v[0:15]
	ds_read_b64_tr_b16 v[220:221], v252 offset:8704
	ds_read_b64_tr_b16 v[222:223], v252 offset:10752
	v_mov_b32_e32 v210, v209
	s_nop 1
	v_permlane32_swap_b32_e32 v209, v210
	v_mov_b32_e32 v211, 1.0
	s_waitcnt lgkmcnt(6)
	v_mfma_f32_32x32x16_bf16 v[0:15], v[156:159], v[224:227], v[0:15]
	ds_read_b64_tr_b16 v[224:225], v252 offset:12800
	ds_read_b64_tr_b16 v[226:227], v252 offset:14848
	s_waitcnt lgkmcnt(6)
	v_mfma_f32_32x32x16_bf16 v[48:63], v[144:147], v[212:215], v[48:63]
	ds_read_b64_tr_b16 v[212:213], v252 offset:1024
	ds_read_b64_tr_b16 v[214:215], v252 offset:3072
	s_waitcnt lgkmcnt(6)
	v_mfma_f32_32x32x16_bf16 v[48:63], v[148:151], v[216:219], v[48:63]
	ds_read_b64_tr_b16 v[216:217], v252 offset:5120
	ds_read_b64_tr_b16 v[218:219], v252 offset:7168
	s_waitcnt lgkmcnt(6)
	v_mfma_f32_32x32x16_bf16 v[48:63], v[152:155], v[220:223], v[48:63]
	ds_read_b64_tr_b16 v[220:221], v252 offset:9216
	ds_read_b64_tr_b16 v[222:223], v252 offset:11264
	s_waitcnt lgkmcnt(6)
	v_mfma_f32_32x32x16_bf16 v[48:63], v[156:159], v[224:227], v[48:63]
	ds_read_b64_tr_b16 v[224:225], v252 offset:13312
	ds_read_b64_tr_b16 v[226:227], v252 offset:15360
	s_waitcnt lgkmcnt(6)
	v_mfma_f32_32x32x16_bf16 v[32:47], v[144:147], v[212:215], v[32:47]
	ds_read_b64_tr_b16 v[212:213], v252 offset:1536
	ds_read_b64_tr_b16 v[214:215], v252 offset:3584
	s_waitcnt lgkmcnt(6)
	v_mfma_f32_32x32x16_bf16 v[32:47], v[148:151], v[216:219], v[32:47]
	ds_read_b64_tr_b16 v[216:217], v252 offset:5632
	ds_read_b64_tr_b16 v[218:219], v252 offset:7680
	s_waitcnt lgkmcnt(6)
	v_mfma_f32_32x32x16_bf16 v[32:47], v[152:155], v[220:223], v[32:47]
	ds_read_b64_tr_b16 v[220:221], v252 offset:9728
	ds_read_b64_tr_b16 v[222:223], v252 offset:11776
	s_waitcnt lgkmcnt(6)
	v_mfma_f32_32x32x16_bf16 v[32:47], v[156:159], v[224:227], v[32:47]
	ds_read_b64_tr_b16 v[224:225], v252 offset:13824
	ds_read_b64_tr_b16 v[226:227], v252 offset:15872
	s_waitcnt lgkmcnt(6)
	v_mfma_f32_32x32x16_bf16 v[16:31], v[144:147], v[212:215], v[16:31]
	v_max_f32_e32 v144, v81, v81
	v_max_f32_e32 v145, v80, v80
	v_max_f32_e32 v144, v145, v144
	v_max3_f32 v144, v144, v82, v83
	v_max3_f32 v144, v144, v84, v85
	v_max3_f32 v144, v144, v86, v87
	v_max3_f32 v144, v144, v88, v89
	s_waitcnt lgkmcnt(4)
	v_mfma_f32_32x32x16_bf16 v[16:31], v[148:151], v[216:219], v[16:31]
	v_max3_f32 v144, v144, v90, v91
	v_max3_f32 v144, v144, v92, v93
	v_max3_f32 v144, v144, v94, v95
	v_max3_f32 v144, v144, v64, v65
	v_max3_f32 v144, v144, v66, v67
	v_max3_f32 v144, v144, v68, v69
	v_max3_f32 v144, v144, v70, v71
	s_waitcnt lgkmcnt(2)
	v_mfma_f32_32x32x16_bf16 v[16:31], v[152:155], v[220:223], v[16:31]
	v_max3_f32 v144, v144, v72, v73
	v_max3_f32 v144, v144, v74, v75
	v_max3_f32 v144, v144, v76, v77
	v_max3_f32 v144, v144, v78, v79
	v_mov_b32_e32 v145, v144
	s_nop 1
	v_permlane32_swap_b32_e32 v144, v145
	s_waitcnt lgkmcnt(0)
	v_mfma_f32_32x32x16_bf16 v[16:31], v[156:159], v[224:227], v[16:31]
	v_max_f32_e32 v145, v145, v145
	v_max_f32_e32 v144, v144, v144
	v_max_f32_e32 v144, v144, v145
	v_sub_f32_e32 v145, v144, v191
	v_cmp_ge_f32_e32 vcc, s35, v145
	s_cmp_eq_u64 vcc, exec
	s_cbranch_scc0 .LBB0_344
	v_cmp_gt_f32_e32 vcc, 1.0, v211
	s_cbranch_vccz .LBB0_336

; #define ISSUE_K(t, slot) do { const char* kg_ = (const char*)(Kh + (long)(t) * (KVBLK * 192)); char* kl_ = K_lds + (slot) * SHM_K + tid * 16; \
;     DMA16(kg_ + kso0, kl_); DMA16(kg_ + kso1, kl_ + 8192); DMA16(kg_ + kso2, kl_ + 16384); } while (0)
; #define ISSUE_V(t, slot) do { const char* vg_ = (const char*)(Vh + (long)(t) * (KVBLK * 128)); char* vl_ = V_lds + (slot) * SHM_V + tid * 16; \
;     DMA16(vg_ + vso0, vl_); DMA16(vg_ + vso1, vl_ + 8192); } while (0)
; #define TBAR(n) do { asm volatile("s_waitcnt vmcnt(" #n ") lgkmcnt(0)" ::: "memory"); __builtin_amdgcn_s_barrier(); SBAR(); } while (0)
; __device__ __forceinline__ void qkt(f32x16& p0, f32x16& p1, const char* Ks, const bf16x8* qr, int r32, int hi) {
;   p0 = f32x16{}; p1 = f32x16{};
; #pragma unroll
;   for (int d0 = 0; d0 < 12; ++d0) { int cb = (d0 * 16 + hi * 8) * 2;
;     bf16x8 b0 = *reinterpret_cast<const bf16x8*>(Ks + KSWZ(r32, cb));
;     bf16x8 b1 = *reinterpret_cast<const bf16x8*>(Ks + KSWZ(32 + r32, cb));
;     p0 = __builtin_amdgcn_mfma_f32_32x32x16_bf16(b0, qr[d0], p0, 0, 0, 0);
;     p1 = __builtin_amdgcn_mfma_f32_32x32x16_bf16(b1, qr[d0], p1, 0, 0, 0); }
; }
; __device__ __forceinline__ void attn_body(const u16* __restrict__ Qb, const u16* __restrict__ Kh, const u16* __restrict__ Vh,
;                                           u16* __restrict__ Ob, int seq, int wvs) {
;     ...
;   f32x16 pA0, pA1, pB0, pB1; float mnA, mnB, alA, alB; bf16x8 pa0, pa1, pa2, pa3; const int NT = seq / KVBLK;
;   ISSUE_K(0, 0); ISSUE_V(0, 0); ISSUE_K(1, 1);
;   TBAR(5);
;   ISSUE_K(2, 2); ISSUE_V(1, 1);
;   qkt(pA0, pA1, K_lds, qr, r32, hi); partialSM(pA0, pA1, m_reg, mnA, alA);
;   int sK = 1, sV = 0;
;   for (int j = 1; j + 1 < NT; j += 2) {
;     TBAR(5);
;     ISSUE_K(j + 2, NEXT3(NEXT3(sK))); ISSUE_V(j + 1, NEXT3(NEXT3(sV)));
;     qkt(pB0, pB1, K_lds + sK * SHM_K, qr, r32, hi);
;     finishSM(pA0, pA1, alA, l_reg, pa0, pa1, pa2, pa3);
;     pv_d0(o, vb0 + sV * SHM_V, pa0, pa1, pa2, pa3); partialSM(pB0, pB1, m_reg, mnB, alB);
;     RESC(alB);
;     sK = NEXT3(sK); sV = NEXT3(sV);
;     TBAR(5);
;     if (j + 3 < NT) ISSUE_K(j + 3, NEXT3(NEXT3(sK)));
;     ISSUE_V(j + 2, NEXT3(NEXT3(sV)));
;     qkt(pA0, pA1, K_lds + sK * SHM_K, qr, r32, hi);
.LBB0_336:
	s_waitcnt vmcnt(5) lgkmcnt(0)
	s_barrier
	s_cmp_ge_u32 s30, s1
	s_cselect_b64 s[10:11], -1, 0
	s_and_b64 vcc, exec, s[10:11]
	s_cbranch_vccnz .LBB0_338
	s_add_i32 s12, s13, 1
	s_and_b64 s[18:19], s[4:5], exec
	s_cselect_b32 s12, 0, s12
	s_mul_i32 s17, s12, 0x6000
	s_addk_i32 s17, 0x6000
	s_cmp_lg_u32 s12, 2
	s_cselect_b32 s12, s17, 0
	s_lshl_b32 vcc_lo, s69, 4
	s_add_i32 vcc_lo, vcc_lo, s12
	s_add_i32 vcc_hi, vcc_lo, 0xc000
	s_mov_b32 m0, vcc_hi
	s_add_i32 vcc_hi, vcc_lo, 0xe000
	global_load_lds_dwordx4 v166, s[98:99]
	s_mov_b32 m0, vcc_hi
	s_add_i32 vcc_hi, vcc_lo, 0x10000
	global_load_lds_dwordx4 v167, s[98:99]
	s_mov_b32 m0, vcc_hi
	s_nop 0
	global_load_lds_dwordx4 v168, s[98:99]
.LBB0_338:
	s_add_u32 s98, s98, 0x6000
	s_addc_u32 s99, s99, 0
	s_add_i32 s16, s16, 1
	s_and_b64 s[8:9], s[8:9], exec
	s_cselect_b32 s12, 0, s16
	s_lshl_b32 s17, s12, 14
	s_add_i32 s8, s17, 0x4000
	s_cmp_lg_u32 s12, 2
	v_mul_f32_e32 v180, 0xbdd53b94, v191
	s_cselect_b32 s16, s8, 0
	v_fmamk_f32 v221, v66, 0x3dd53b94, v180
	v_fmamk_f32 v219, v64, 0x3dd53b94, v180
	v_fmamk_f32 v220, v65, 0x3dd53b94, v180
	s_lshl_b32 vcc_lo, s69, 4
	s_add_i32 vcc_lo, vcc_lo, s16
	s_mov_b32 m0, vcc_lo
	s_add_i32 vcc_hi, vcc_lo, 0x2000
	global_load_lds_dwordx4 v169, s[100:101]
	s_mov_b32 m0, vcc_hi
	s_add_i32 s8, s15, 0
	v_fmamk_f32 v218, v68, 0x3dd53b94, v180
	global_load_lds_dwordx4 v170, s[100:101]
	s_add_u32 s100, s100, 0x4000
	s_addc_u32 s101, s101, 0
	v_add_u32_e32 v68, s8, v193
	v_fmamk_f32 v217, v67, 0x3dd53b94, v180
	v_fmamk_f32 v181, v69, 0x3dd53b94, v180
	v_fmamk_f32 v182, v70, 0x3dd53b94, v180
	v_fmamk_f32 v183, v71, 0x3dd53b94, v180
	ds_read_b128 v[64:67], v68 offset:49152
	ds_read_b128 v[68:71], v68 offset:61440
	v_add_u32_e32 v162, s8, v193
	v_add_u32_e32 v253, s8, v199
	v_add_u32_e32 v252, s8, v200
	v_add_u32_e32 v244, s8, v202
	ds_read_b128 v[176:179], v253 offset:49152
	ds_read_b128 v[222:225], v253 offset:61440
	v_fmamk_f32 v80, v80, 0x3dd53b94, v180
	v_fmamk_f32 v81, v81, 0x3dd53b94, v180
	v_fmamk_f32 v82, v82, 0x3dd53b94, v180
	v_fmamk_f32 v83, v83, 0x3dd53b94, v180
	v_fmamk_f32 v84, v84, 0x3dd53b94, v180
	v_fmamk_f32 v85, v85, 0x3dd53b94, v180
	v_fmamk_f32 v86, v86, 0x3dd53b94, v180
	v_fmamk_f32 v87, v87, 0x3dd53b94, v180
	v_fmamk_f32 v88, v88, 0x3dd53b94, v180
	v_fmamk_f32 v89, v89, 0x3dd53b94, v180
	v_fmamk_f32 v90, v90, 0x3dd53b94, v180
	v_fmamk_f32 v91, v91, 0x3dd53b94, v180
	v_fmamk_f32 v92, v92, 0x3dd53b94, v180
	v_fmamk_f32 v93, v93, 0x3dd53b94, v180
	v_fmamk_f32 v94, v94, 0x3dd53b94, v180
	v_fmamk_f32 v95, v95, 0x3dd53b94, v180
	v_exp_f32_e32 v144, v80
	v_exp_f32_e32 v145, v81
	v_exp_f32_e32 v146, v82
	v_exp_f32_e32 v156, v83
	v_exp_f32_e32 v147, v84
	v_exp_f32_e32 v157, v85
	v_exp_f32_e32 v158, v86
	v_exp_f32_e32 v159, v87
	v_exp_f32_e32 v148, v88
	v_exp_f32_e32 v150, v89
	v_exp_f32_e32 v149, v90
	v_exp_f32_e32 v151, v91
	v_exp_f32_e32 v152, v92
	v_exp_f32_e32 v153, v93
	v_exp_f32_e32 v154, v94
	v_exp_f32_e32 v155, v95
	s_waitcnt lgkmcnt(2)
	v_mfma_f32_32x32x16_bf16 v[80:95], v[64:67], v[140:143], 0
	ds_read_b128 v[236:239], v252 offset:49152
	ds_read_b128 v[240:243], v252 offset:61440
	v_fmamk_f32 v184, v72, 0x3dd53b94, v180
	v_fmamk_f32 v185, v73, 0x3dd53b94, v180
	v_fmamk_f32 v212, v74, 0x3dd53b94, v180
	v_fmamk_f32 v213, v75, 0x3dd53b94, v180
	v_fmamk_f32 v214, v76, 0x3dd53b94, v180
	v_fmamk_f32 v215, v77, 0x3dd53b94, v180
	v_fmamk_f32 v216, v78, 0x3dd53b94, v180
	v_fmac_f32_e32 v180, 0x3dd53b94, v79
	v_mfma_f32_32x32x16_bf16 v[64:79], v[68:71], v[140:143], 0
	v_exp_f32_e32 v163, v220
	v_exp_f32_e32 v206, v218
	v_exp_f32_e32 v181, v181
	v_exp_f32_e32 v182, v182
	v_exp_f32_e32 v183, v183
	s_waitcnt lgkmcnt(2)
	v_mfma_f32_32x32x16_bf16 v[80:95], v[176:179], v[136:139], v[80:95]
	v_exp_f32_e32 v184, v184
	v_exp_f32_e32 v185, v185
	v_exp_f32_e32 v212, v212
	v_exp_f32_e32 v213, v213
	v_exp_f32_e32 v214, v214
	v_exp_f32_e32 v215, v215
	v_exp_f32_e32 v216, v216
	v_mfma_f32_32x32x16_bf16 v[64:79], v[222:225], v[136:139], v[64:79]
	ds_read_b128 v[176:179], v244 offset:49152
	ds_read_b128 v[222:225], v244 offset:61440
	v_exp_f32_e32 v180, v180
	s_waitcnt lgkmcnt(2)
	v_mfma_f32_32x32x16_bf16 v[80:95], v[236:239], v[132:135], v[80:95]
	v_mfma_f32_32x32x16_bf16 v[64:79], v[240:243], v[132:135], v[64:79]
	ds_read_b128 v[236:239], v162 offset:49280
	ds_read_b128 v[240:243], v162 offset:61568
	s_waitcnt lgkmcnt(2)
	v_mfma_f32_32x32x16_bf16 v[80:95], v[176:179], v[128:131], v[80:95]
	v_mfma_f32_32x32x16_bf16 v[64:79], v[222:225], v[128:131], v[64:79]
	ds_read_b128 v[176:179], v253 offset:49280
	ds_read_b128 v[222:225], v253 offset:61568
	s_waitcnt lgkmcnt(2)
	v_mfma_f32_32x32x16_bf16 v[80:95], v[236:239], v[124:127], v[80:95]
	v_mfma_f32_32x32x16_bf16 v[64:79], v[240:243], v[124:127], v[64:79]
	ds_read_b128 v[236:239], v252 offset:49280
	ds_read_b128 v[240:243], v252 offset:61568
	s_waitcnt lgkmcnt(2)
	v_mfma_f32_32x32x16_bf16 v[80:95], v[176:179], v[120:123], v[80:95]
	v_mfma_f32_32x32x16_bf16 v[64:79], v[222:225], v[120:123], v[64:79]
	ds_read_b128 v[176:179], v244 offset:49280
	ds_read_b128 v[222:225], v244 offset:61568
	s_waitcnt lgkmcnt(2)
	v_mfma_f32_32x32x16_bf16 v[80:95], v[236:239], v[116:119], v[80:95]
	v_mfma_f32_32x32x16_bf16 v[64:79], v[240:243], v[116:119], v[64:79]
	ds_read_b128 v[236:239], v162 offset:49408
	ds_read_b128 v[240:243], v162 offset:61696
	s_waitcnt lgkmcnt(2)
	v_mfma_f32_32x32x16_bf16 v[80:95], v[176:179], v[112:115], v[80:95]
	v_mfma_f32_32x32x16_bf16 v[64:79], v[222:225], v[112:115], v[64:79]
	ds_read_b128 v[176:179], v253 offset:49408
	ds_read_b128 v[222:225], v253 offset:61696
	s_waitcnt lgkmcnt(2)
; __device__ __forceinline__ void finishSM(f32x16& p0, f32x16& p1, float alpha, float& l_reg, bf16x8& pa0, bf16x8& pa1, bf16x8& pa2, bf16x8& pa3) {
;   for (int r = 0; r < 16; ++r) p1[r] = __builtin_amdgcn_exp2f(p1[r]);
;   float ps = 0; for (int r = 0; r < 16; ++r) ps += p0[r]; for (int r = 0; r < 16; ++r) ps += p1[r];
;   { auto rr = __builtin_amdgcn_permlane32_swap(__float_as_uint(ps), __float_as_uint(ps), false, false);
;     ps = __uint_as_float(rr[0]) + __uint_as_float(rr[1]); }
;   l_reg = l_reg * alpha + ps;
;     ...
;   PK4(p0, 0, pa0); PK4(p0, 8, pa1); PK4(p1, 0, pa2); PK4(p1, 8, pa3);
;     ...
; }
; __device__ __forceinline__ void qkt(f32x16& p0, f32x16& p1, const char* Ks, const bf16x8* qr, int r32, int hi) {
;   p0 = f32x16{}; p1 = f32x16{};
; #pragma unroll
;   for (int d0 = 0; d0 < 12; ++d0) { int cb = (d0 * 16 + hi * 8) * 2;
;     bf16x8 b0 = *reinterpret_cast<const bf16x8*>(Ks + KSWZ(r32, cb));
;     bf16x8 b1 = *reinterpret_cast<const bf16x8*>(Ks + KSWZ(32 + r32, cb));
;     p0 = __builtin_amdgcn_mfma_f32_32x32x16_bf16(b0, qr[d0], p0, 0, 0, 0);
;     p1 = __builtin_amdgcn_mfma_f32_32x32x16_bf16(b1, qr[d0], p1, 0, 0, 0); }
; }
; __device__ __forceinline__ int v_st(int k, int c) { const int kk = (k & ~0xC) | ((k & 4) << 1) | ((k & 8) >> 1); return ((kk >> 3) * 4 + (c >> 5)) * 512 + ((kk & 7) * 32 + (c & 31)) * 2; }
; __device__ __forceinline__ int v_rd_base(int lane) { return ((lane & 3) << 3) | (((lane >> 2) & 3) << 6) | (((lane >> 4) & 1) << 5) | (((lane >> 5) & 1) << 8); }
; template <int OFF> __device__ __forceinline__ s16x4 tr_read(int vb) {
;   return __builtin_amdgcn_ds_read_tr16_b64_v4i16((lds_s16x4*)(uintptr_t)(unsigned)(vb + OFF));
; }
; template <int D0> __device__ __forceinline__ void pv_one(f32x16& od, int vb, bf16x8 pa0, bf16x8 pa1, bf16x8 pa2, bf16x8 pa3) {
;   const s16x4 l0 = tr_read<v_rd_off(D0, 0, 0)>(vb), h0 = tr_read<v_rd_off(D0, 0, 1)>(vb), l1 = tr_read<v_rd_off(D0, 1, 0)>(vb), h1 = tr_read<v_rd_off(D0, 1, 1)>(vb);
;   const s16x4 l2 = tr_read<v_rd_off(D0, 2, 0)>(vb), h2 = tr_read<v_rd_off(D0, 2, 1)>(vb), l3 = tr_read<v_rd_off(D0, 3, 0)>(vb), h3 = tr_read<v_rd_off(D0, 3, 1)>(vb);
;     ...
;   od = __builtin_amdgcn_mfma_f32_32x32x16_bf16(pa0, PK(l0, h0), od, 0, 0, 0);
;   od = __builtin_amdgcn_mfma_f32_32x32x16_bf16(pa1, PK(l1, h1), od, 0, 0, 0);
;   od = __builtin_amdgcn_mfma_f32_32x32x16_bf16(pa2, PK(l2, h2), od, 0, 0, 0);
	v_mfma_f32_32x32x16_bf16 v[80:95], v[236:239], v[108:111], v[80:95]
	v_mfma_f32_32x32x16_bf16 v[64:79], v[240:243], v[108:111], v[64:79]
	ds_read_b128 v[236:239], v252 offset:49408
	ds_read_b128 v[240:243], v252 offset:61696
	s_waitcnt lgkmcnt(2)
	v_mfma_f32_32x32x16_bf16 v[80:95], v[176:179], v[104:107], v[80:95]
	v_mfma_f32_32x32x16_bf16 v[64:79], v[222:225], v[104:107], v[64:79]
	ds_read_b128 v[176:179], v244 offset:49408
	ds_read_b128 v[222:225], v244 offset:61696
	v_add_u32_e32 v252, s14, v190
	ds_read_b64_tr_b16 v[244:245], v252
	ds_read_b64_tr_b16 v[246:247], v252 offset:2048
	ds_read_b64_tr_b16 v[248:249], v252 offset:4096
	ds_read_b64_tr_b16 v[250:251], v252 offset:6144
	v_exp_f32_e32 v162, v219
	s_waitcnt lgkmcnt(6)
	v_mfma_f32_32x32x16_bf16 v[80:95], v[236:239], v[100:103], v[80:95]
	v_mfma_f32_32x32x16_bf16 v[64:79], v[240:243], v[100:103], v[64:79]
	s_waitcnt lgkmcnt(4)
	v_mfma_f32_32x32x16_bf16 v[80:95], v[176:179], v[96:99], v[80:95]
	v_add_f32_e32 v177, 0, v144
	v_add_f32_e32 v177, v145, v177
	v_add_f32_e32 v177, v146, v177
	v_add_f32_e32 v177, v156, v177
	v_add_f32_e32 v177, v147, v177
	v_add_f32_e32 v177, v157, v177
	v_add_f32_e32 v177, v158, v177
	v_add_f32_e32 v177, v159, v177
	v_add_f32_e32 v177, v148, v177
	v_add_f32_e32 v177, v150, v177
	v_add_f32_e32 v177, v149, v177
	v_add_f32_e32 v177, v151, v177
	v_add_f32_e32 v177, v152, v177
	v_add_f32_e32 v177, v153, v177
	v_exp_f32_e32 v176, v221
	v_add_f32_e32 v177, v154, v177
	v_exp_f32_e32 v179, v217
	v_add_f32_e32 v177, v155, v177
	v_add_f32_e32 v177, v162, v177
	v_add_f32_e32 v177, v163, v177
	v_add_f32_e32 v177, v176, v177
	v_add_f32_e32 v177, v179, v177
	v_add_f32_e32 v177, v206, v177
	v_add_f32_e32 v177, v181, v177
	v_add_f32_e32 v177, v182, v177
	v_add_f32_e32 v177, v183, v177
	v_add_f32_e32 v177, v184, v177
	v_add_f32_e32 v177, v185, v177
	v_cvt_pk_bf16_f32 v144, v144, v145
	v_cvt_pk_bf16_f32 v145, v146, v156
	v_cvt_pk_bf16_f32 v146, v147, v157
	v_cvt_pk_bf16_f32 v147, v158, v159
	v_add_f32_e32 v177, v212, v177
	v_permlane32_swap_b32_e32 v144, v146
	v_permlane32_swap_b32_e32 v145, v147
	v_add_f32_e32 v177, v213, v177
	v_add_f32_e32 v177, v214, v177
	v_add_f32_e32 v177, v215, v177
	v_add_f32_e32 v177, v216, v177
	v_cvt_pk_bf16_f32 v148, v148, v150
	v_cvt_pk_bf16_f32 v150, v152, v153
	v_cvt_pk_bf16_f32 v152, v162, v163
	v_mfma_f32_32x32x16_bf16 v[64:79], v[222:225], v[96:99], v[64:79]
	v_add_f32_e32 v177, v180, v177
	v_cvt_pk_bf16_f32 v149, v149, v151
	v_cvt_pk_bf16_f32 v151, v154, v155
	v_cvt_pk_bf16_f32 v154, v206, v181
	v_cvt_pk_bf16_f32 v155, v182, v183
	v_cvt_pk_bf16_f32 v157, v212, v213
	v_cvt_pk_bf16_f32 v158, v214, v215
	v_cvt_pk_bf16_f32 v159, v216, v180
	ds_read_b64_tr_b16 v[216:217], v252 offset:8192
	ds_read_b64_tr_b16 v[218:219], v252 offset:10240
	ds_read_b64_tr_b16 v[220:221], v252 offset:12288
	ds_read_b64_tr_b16 v[222:223], v252 offset:14336
	s_waitcnt lgkmcnt(4)
	v_mfma_f32_32x32x16_bf16 v[0:15], v[144:147], v[244:247], v[0:15]
	ds_read_b64_tr_b16 v[180:181], v252 offset:512
	ds_read_b64_tr_b16 v[182:183], v252 offset:2560
	v_permlane32_swap_b32_e32 v148, v150
	v_permlane32_swap_b32_e32 v149, v151
	v_cvt_pk_bf16_f32 v153, v176, v179
	v_permlane32_swap_b32_e32 v152, v154
	v_mfma_f32_32x32x16_bf16 v[0:15], v[148:151], v[248:251], v[0:15]
	ds_read_b64_tr_b16 v[212:213], v252 offset:4608
	ds_read_b64_tr_b16 v[214:215], v252 offset:6656
	v_permlane32_swap_b32_e32 v153, v155
	v_cvt_pk_bf16_f32 v156, v184, v185
	s_nop 1
	v_permlane32_swap_b32_e32 v156, v158
	v_permlane32_swap_b32_e32 v157, v159
	s_waitcnt lgkmcnt(6)
	v_mfma_f32_32x32x16_bf16 v[0:15], v[152:155], v[216:219], v[0:15]
	ds_read_b64_tr_b16 v[216:217], v252 offset:8704
	ds_read_b64_tr_b16 v[218:219], v252 offset:10752
	v_mov_b32_e32 v178, v177
	s_nop 1
	v_permlane32_swap_b32_e32 v177, v178
	s_waitcnt lgkmcnt(6)
	v_mfma_f32_32x32x16_bf16 v[0:15], v[156:159], v[220:223], v[0:15]
	ds_read_b64_tr_b16 v[220:221], v252 offset:12800
	ds_read_b64_tr_b16 v[222:223], v252 offset:14848
	s_waitcnt lgkmcnt(6)
	v_mfma_f32_32x32x16_bf16 v[48:63], v[144:147], v[180:183], v[48:63]
	ds_read_b64_tr_b16 v[180:181], v252 offset:1024
	ds_read_b64_tr_b16 v[182:183], v252 offset:3072
	s_waitcnt lgkmcnt(6)
	v_mfma_f32_32x32x16_bf16 v[48:63], v[148:151], v[212:215], v[48:63]
	ds_read_b64_tr_b16 v[212:213], v252 offset:5120
	ds_read_b64_tr_b16 v[214:215], v252 offset:7168
	s_waitcnt lgkmcnt(6)
	v_mfma_f32_32x32x16_bf16 v[48:63], v[152:155], v[216:219], v[48:63]
	ds_read_b64_tr_b16 v[216:217], v252 offset:9216
	ds_read_b64_tr_b16 v[218:219], v252 offset:11264
	s_waitcnt lgkmcnt(6)
	v_mfma_f32_32x32x16_bf16 v[48:63], v[156:159], v[220:223], v[48:63]
	ds_read_b64_tr_b16 v[220:221], v252 offset:13312
	ds_read_b64_tr_b16 v[222:223], v252 offset:15360
	s_waitcnt lgkmcnt(6)
	v_mfma_f32_32x32x16_bf16 v[32:47], v[144:147], v[180:183], v[32:47]
	ds_read_b64_tr_b16 v[180:181], v252 offset:1536
	ds_read_b64_tr_b16 v[182:183], v252 offset:3584
	s_waitcnt lgkmcnt(6)
	v_mfma_f32_32x32x16_bf16 v[32:47], v[148:151], v[212:215], v[32:47]
	ds_read_b64_tr_b16 v[212:213], v252 offset:5632
	ds_read_b64_tr_b16 v[214:215], v252 offset:7680
	s_waitcnt lgkmcnt(6)
	v_mfma_f32_32x32x16_bf16 v[32:47], v[152:155], v[216:219], v[32:47]
	ds_read_b64_tr_b16 v[216:217], v252 offset:9728
	ds_read_b64_tr_b16 v[218:219], v252 offset:11776
	s_waitcnt lgkmcnt(6)
	v_mfma_f32_32x32x16_bf16 v[32:47], v[156:159], v[220:223], v[32:47]
	ds_read_b64_tr_b16 v[220:221], v252 offset:13824
	ds_read_b64_tr_b16 v[222:223], v252 offset:15872
	s_waitcnt lgkmcnt(6)
	v_mfma_f32_32x32x16_bf16 v[16:31], v[144:147], v[180:183], v[16:31]
	v_max_f32_e32 v144, v81, v81
	v_max_f32_e32 v145, v80, v80
	v_max_f32_e32 v144, v145, v144
	v_max3_f32 v144, v144, v82, v83
	v_max3_f32 v144, v144, v84, v85
	v_max3_f32 v144, v144, v86, v87
	v_max3_f32 v144, v144, v88, v89
	v_max3_f32 v144, v144, v90, v91
	v_max3_f32 v144, v144, v92, v93
	s_waitcnt lgkmcnt(4)
	v_mfma_f32_32x32x16_bf16 v[16:31], v[148:151], v[212:215], v[16:31]
	v_max3_f32 v144, v144, v94, v95
	v_max3_f32 v144, v144, v64, v65
	v_max3_f32 v144, v144, v66, v67
	v_max3_f32 v144, v144, v68, v69
	v_max3_f32 v144, v144, v70, v71
	v_max3_f32 v144, v144, v72, v73
	v_max3_f32 v144, v144, v74, v75
	v_max3_f32 v144, v144, v76, v77
	s_waitcnt lgkmcnt(2)
	v_mfma_f32_32x32x16_bf16 v[16:31], v[152:155], v[216:219], v[16:31]
	v_max3_f32 v144, v144, v78, v79
	v_mov_b32_e32 v145, v144
	s_nop 1
	v_permlane32_swap_b32_e32 v144, v145
	v_max_f32_e32 v145, v145, v145
	v_max_f32_e32 v144, v144, v144
	v_max_f32_e32 v144, v144, v145
	v_sub_f32_e32 v145, v144, v191
	v_cmp_ge_f32_e32 vcc, s35, v145
	v_max_f32_e32 v145, v191, v191
	v_max_f32_e32 v144, v145, v144
	s_waitcnt lgkmcnt(0)
	v_mfma_f32_32x32x16_bf16 v[16:31], v[156:159], v[220:223], v[16:31]
	v_sub_f32_e32 v145, v191, v144
	v_mul_f32_e32 v145, 0x3dd53b94, v145
	v_exp_f32_e32 v145, v145
	s_cmp_eq_u64 vcc, exec
	s_cselect_b64 s[8:9], -1, 0
	v_cndmask_b32_e64 v176, v145, 1.0, s[8:9]
	v_cmp_gt_f32_e32 vcc, 1.0, v176
	s_cbranch_vccz .LBB0_342
; __device__ __forceinline__ void partialSM(f32x16& p0, f32x16& p1, float& m_reg, float& mn, float& alpha) {
;   constexpr float C = ASCALE * 1.4426950408889634f;
;   float pmax = p0[0]; for (int r = 1; r < 16; ++r) pmax = fmaxf(pmax, p0[r]); for (int r = 0; r < 16; ++r) pmax = fmaxf(pmax, p1[r]);
;   { auto rr = __builtin_amdgcn_permlane32_swap(__float_as_uint(pmax), __float_as_uint(pmax), false, false);
;     pmax = fmaxf(__uint_as_float(rr[0]), __uint_as_float(rr[1])); }
;   if (__builtin_expect(__all(pmax - m_reg <= THR / ASCALE), 1)) { mn = m_reg; alpha = 1.f; }
;   else { mn = fmaxf(m_reg, pmax); alpha = __builtin_amdgcn_exp2f((m_reg - mn) * C); m_reg = mn; }
;   float mnC = -mn * C;
;   for (int r = 0; r < 16; ++r) p0[r] = fmaf(p0[r], C, mnC); for (int r = 0; r < 16; ++r) p1[r] = fmaf(p1[r], C, mnC);
;   for (int r = 0; r < 16; ++r) p0[r] = __builtin_amdgcn_exp2f(p0[r]);
; }
; __device__ __forceinline__ void finishSM(f32x16& p0, f32x16& p1, float alpha, float& l_reg, bf16x8& pa0, bf16x8& pa1, bf16x8& pa2, bf16x8& pa3) {
;   for (int r = 0; r < 16; ++r) p1[r] = __builtin_amdgcn_exp2f(p1[r]);
;   float ps = 0; for (int r = 0; r < 16; ++r) ps += p0[r]; for (int r = 0; r < 16; ++r) ps += p1[r];
;   { auto rr = __builtin_amdgcn_permlane32_swap(__float_as_uint(ps), __float_as_uint(ps), false, false);
;     ps = __uint_as_float(rr[0]) + __uint_as_float(rr[1]); }
;   l_reg = l_reg * alpha + ps;
; __device__ __forceinline__ void attn_body(const u16* __restrict__ Qb, const u16* __restrict__ Kh, const u16* __restrict__ Vh,
;                                           u16* __restrict__ Ob, int seq, int wvs) {
;     ...
;   f32x16 pA0, pA1, pB0, pB1; float mnA, mnB, alA, alB; bf16x8 pa0, pa1, pa2, pa3; const int NT = seq / KVBLK;
;   ISSUE_K(0, 0); ISSUE_V(0, 0); ISSUE_K(1, 1);
;   TBAR(5);
;   ISSUE_K(2, 2); ISSUE_V(1, 1);
;   qkt(pA0, pA1, K_lds, qr, r32, hi); partialSM(pA0, pA1, m_reg, mnA, alA);
;   int sK = 1, sV = 0;
;   for (int j = 1; j + 1 < NT; j += 2) {
;     TBAR(5);
;     ISSUE_K(j + 2, NEXT3(NEXT3(sK))); ISSUE_V(j + 1, NEXT3(NEXT3(sV)));
;     qkt(pB0, pB1, K_lds + sK * SHM_K, qr, r32, hi);
;     finishSM(pA0, pA1, alA, l_reg, pa0, pa1, pa2, pa3);
;     pv_d0(o, vb0 + sV * SHM_V, pa0, pa1, pa2, pa3); partialSM(pB0, pB1, m_reg, mnB, alB);
;     RESC(alB);
;     sK = NEXT3(sK); sV = NEXT3(sV);
;     TBAR(5);
	s_and_saveexec_b64 s[14:15], s[6:7]
	ds_write_b32 v188, v176 offset:128
	s_or_b64 exec, exec, s[14:15]
	s_waitcnt lgkmcnt(0)
	v_add_u32_e32 v145, v165, v160
	ds_read_b128 v[146:149], v145 offset:224
	ds_read_b128 v[150:153], v145 offset:192
	ds_read_b128 v[154:157], v145 offset:160
	ds_read_b128 v[180:183], v145 offset:128
	s_waitcnt lgkmcnt(0)
	v_pk_mul_f32 v[12:13], v[12:13], v[146:147]
	v_pk_mul_f32 v[8:9], v[8:9], v[150:151]
	v_pk_mul_f32 v[4:5], v[4:5], v[154:155]
	v_pk_mul_f32 v[14:15], v[14:15], v[148:149]
	v_pk_mul_f32 v[10:11], v[10:11], v[152:153]
	v_pk_mul_f32 v[6:7], v[6:7], v[156:157]
	v_pk_mul_f32 v[2:3], v[2:3], v[182:183]
	v_pk_mul_f32 v[0:1], v[0:1], v[180:181]
	v_pk_mul_f32 v[60:61], v[60:61], v[146:147]
	v_pk_mul_f32 v[56:57], v[56:57], v[150:151]
	v_pk_mul_f32 v[52:53], v[52:53], v[154:155]
	v_pk_mul_f32 v[62:63], v[62:63], v[148:149]
	v_pk_mul_f32 v[58:59], v[58:59], v[152:153]
	v_pk_mul_f32 v[54:55], v[54:55], v[156:157]
	v_pk_mul_f32 v[50:51], v[50:51], v[182:183]
	v_pk_mul_f32 v[48:49], v[48:49], v[180:181]
	v_pk_mul_f32 v[44:45], v[44:45], v[146:147]
	v_pk_mul_f32 v[40:41], v[40:41], v[150:151]
	v_pk_mul_f32 v[36:37], v[36:37], v[154:155]
	v_pk_mul_f32 v[46:47], v[46:47], v[148:149]
	v_pk_mul_f32 v[42:43], v[42:43], v[152:153]
	v_pk_mul_f32 v[38:39], v[38:39], v[156:157]
	v_pk_mul_f32 v[34:35], v[34:35], v[182:183]
	v_pk_mul_f32 v[32:33], v[32:33], v[180:181]
	v_pk_mul_f32 v[28:29], v[28:29], v[146:147]
	v_pk_mul_f32 v[24:25], v[24:25], v[150:151]
	v_pk_mul_f32 v[20:21], v[20:21], v[154:155]
	v_pk_mul_f32 v[30:31], v[30:31], v[148:149]
	v_pk_mul_f32 v[26:27], v[26:27], v[152:153]
	v_pk_mul_f32 v[22:23], v[22:23], v[156:157]
	v_pk_mul_f32 v[18:19], v[18:19], v[182:183]
	v_pk_mul_f32 v[16:17], v[16:17], v[180:181]
.LBB0_342:
	v_cndmask_b32_e64 v191, v144, v191, s[8:9]
	v_mul_f32_e32 v144, 0xbdd53b94, v191
	v_add_f32_e32 v145, v209, v210
	v_mov_b32_e32 v162, v144
	v_fmac_f32_e32 v145, v208, v189
	v_add_f32_e32 v189, v177, v178
	v_fmamk_f32 v80, v80, 0x3dd53b94, v144
	v_fmamk_f32 v81, v81, 0x3dd53b94, v144
	v_fmamk_f32 v82, v82, 0x3dd53b94, v144
	v_fmamk_f32 v83, v83, 0x3dd53b94, v144
	v_fmamk_f32 v84, v84, 0x3dd53b94, v144
	v_fmamk_f32 v85, v85, 0x3dd53b94, v144
	v_fmamk_f32 v86, v86, 0x3dd53b94, v144
	v_fmamk_f32 v87, v87, 0x3dd53b94, v144
	v_fmamk_f32 v88, v88, 0x3dd53b94, v144
	v_fmamk_f32 v89, v89, 0x3dd53b94, v144
	v_fmamk_f32 v90, v90, 0x3dd53b94, v144
	v_fmamk_f32 v91, v91, 0x3dd53b94, v144
	v_fmamk_f32 v92, v92, 0x3dd53b94, v144
	v_fmamk_f32 v93, v93, 0x3dd53b94, v144
	v_fmamk_f32 v94, v94, 0x3dd53b94, v144
	v_fmac_f32_e32 v162, 0x3dd53b94, v95
	v_fmac_f32_e32 v189, v145, v211
	v_exp_f32_e32 v218, v80
	v_exp_f32_e32 v220, v81
	v_exp_f32_e32 v221, v82
	v_exp_f32_e32 v222, v83
	v_exp_f32_e32 v223, v84
	v_exp_f32_e32 v225, v85
	v_exp_f32_e32 v224, v86
	v_exp_f32_e32 v226, v87
	v_exp_f32_e32 v211, v88
	v_exp_f32_e32 v212, v89
	v_exp_f32_e32 v213, v90
	v_exp_f32_e32 v215, v91
	v_exp_f32_e32 v214, v92
	v_exp_f32_e32 v216, v93
	v_exp_f32_e32 v217, v94
	v_exp_f32_e32 v219, v162
	s_add_i32 s13, s13, 1
	s_and_b64 s[4:5], s[4:5], exec
	v_pk_fma_f32 v[158:159], v[64:65], s[68:69], v[144:145] op_sel_hi:[1,0,0]
	v_pk_fma_f32 v[156:157], v[66:67], s[68:69], v[144:145] op_sel_hi:[1,0,0]
	v_pk_fma_f32 v[154:155], v[68:69], s[68:69], v[144:145] op_sel_hi:[1,0,0]
	v_pk_fma_f32 v[152:153], v[70:71], s[68:69], v[144:145] op_sel_hi:[1,0,0]
	v_pk_fma_f32 v[150:151], v[72:73], s[68:69], v[144:145] op_sel_hi:[1,0,0]
	v_pk_fma_f32 v[148:149], v[74:75], s[68:69], v[144:145] op_sel_hi:[1,0,0]
	v_pk_fma_f32 v[146:147], v[76:77], s[68:69], v[144:145] op_sel_hi:[1,0,0]
	v_pk_fma_f32 v[144:145], v[78:79], s[68:69], v[144:145] op_sel_hi:[1,0,0]
	s_cselect_b32 s31, 0, s13
	s_add_i32 s30, s30, 2
	s_and_b64 vcc, exec, s[10:11]
	s_cbranch_vccnz .LBB0_372
	v_mov_b32_e32 v208, v176
	s_branch .LBB0_331

; __global__ void __launch_bounds__(NTHR) mega(Params pin) {
;   cg::grid_group grid = cg::this_grid();
;   const int wvs0 = __builtin_amdgcn_readfirstlane(threadIdx.x >> 6);
	.amdhsa_kernel _Z4mega6Params
		.amdhsa_group_segment_fixed_size 0
		.amdhsa_private_segment_fixed_size 0
		.amdhsa_kernarg_size 472
		.amdhsa_user_sgpr_count 2
		.amdhsa_user_sgpr_dispatch_ptr 0
		.amdhsa_user_sgpr_queue_ptr 0
		.amdhsa_user_sgpr_kernarg_segment_ptr 1
		.amdhsa_user_sgpr_dispatch_id 0
		.amdhsa_user_sgpr_kernarg_preload_length 0
		.amdhsa_user_sgpr_kernarg_preload_offset 0
		.amdhsa_user_sgpr_private_segment_size 0
		.amdhsa_uses_dynamic_stack 0
		.amdhsa_enable_private_segment 0
		.amdhsa_system_sgpr_workgroup_id_x 1
		.amdhsa_system_sgpr_workgroup_id_y 0
		.amdhsa_system_sgpr_workgroup_id_z 0
		.amdhsa_system_sgpr_workgroup_info 0
		.amdhsa_system_vgpr_workitem_id 2
		.amdhsa_next_free_vgpr 256
		.amdhsa_next_free_sgpr 102
		.amdhsa_accum_offset 256
		.amdhsa_reserve_vcc 1
		.amdhsa_float_round_mode_32 0
		.amdhsa_float_round_mode_16_64 0
		.amdhsa_float_denorm_mode_32 3
		.amdhsa_float_denorm_mode_16_64 3
		.amdhsa_dx10_clamp 1
		.amdhsa_ieee_mode 1
		.amdhsa_fp16_overflow 0
		.amdhsa_tg_split 0
		.amdhsa_exception_fp_ieee_invalid_op 0
		.amdhsa_exception_fp_denorm_src 0
		.amdhsa_exception_fp_ieee_div_zero 0
		.amdhsa_exception_fp_ieee_overflow 0
		.amdhsa_exception_fp_ieee_underflow 0
		.amdhsa_exception_fp_ieee_inexact 0
		.amdhsa_exception_int_div_zero 0
	.end_amdhsa_kernel

; __global__ void __launch_bounds__(NTHR) mega(Params pin) {
amdhsa.kernels:
  - .agpr_count:     0
    .args:
      - .offset:         0
        .size:           216
        .value_kind:     by_value
      - .offset:         216
        .size:           4
        .value_kind:     hidden_block_count_x
      - .offset:         220
        .size:           4
        .value_kind:     hidden_block_count_y
      - .offset:         224
        .size:           4
        .value_kind:     hidden_block_count_z
      - .offset:         228
        .size:           2
        .value_kind:     hidden_group_size_x
      - .offset:         230
        .size:           2
        .value_kind:     hidden_group_size_y
      - .offset:         232
        .size:           2
        .value_kind:     hidden_group_size_z
      - .offset:         234
        .size:           2
        .value_kind:     hidden_remainder_x
      - .offset:         236
        .size:           2
        .value_kind:     hidden_remainder_y
      - .offset:         238
        .size:           2
        .value_kind:     hidden_remainder_z
      - .offset:         256
        .size:           8
        .value_kind:     hidden_global_offset_x
      - .offset:         264
        .size:           8
        .value_kind:     hidden_global_offset_y
      - .offset:         272
        .size:           8
        .value_kind:     hidden_global_offset_z
      - .offset:         280
        .size:           2
        .value_kind:     hidden_grid_dims
      - .offset:         304
        .size:           8
        .value_kind:     hidden_multigrid_sync_arg
      - .offset:         336
        .size:           4
        .value_kind:     hidden_dynamic_lds_size
    .group_segment_fixed_size: 0
    .kernarg_segment_align: 8
    .kernarg_segment_size: 472
    .language:       OpenCL C
    .language_version:
      - 2
      - 0
    .max_flat_workgroup_size: 512
    .name:           _Z4mega6Params
    .private_segment_fixed_size: 0
    .sgpr_count:     108
    .sgpr_spill_count: 147
    .symbol:         _Z4mega6Params.kd
    .uniform_work_group_size: 1
    .uses_dynamic_stack: false
    .vgpr_count:     256
    .vgpr_spill_count: 0
    .wavefront_size: 64
